# s5_s1: both halves' u rows loaded with the group's operands (one round trip per group instead of three)
# baseline (speedup 1.0000x reference)
.LBB0_1048:
	s_add_i32 s6, s11, s1
	s_add_i32 s34, s6, s60
	s_ashr_i32 s35, s34, 31
	s_lshl_b64 s[38:39], s[34:35], 10
	s_lshl_b64 s[34:35], s[34:35], 12
	v_lshl_add_u64 v[2:3], v[38:39], 0, s[38:39]
	v_lshl_add_u64 v[30:31], v[40:41], 0, s[34:35]
	flat_load_dwordx2 v[46:47], v[2:3]
	s_nop 0
	flat_load_dwordx4 v[2:5], v[30:31]
	flat_load_dwordx4 v[6:9], v[30:31] offset:512
	flat_load_dwordx4 v[10:13], v[30:31] offset:1024
	flat_load_dwordx4 v[14:17], v[30:31] offset:1536
	flat_load_dwordx4 v[18:21], v[30:31] offset:2048
	flat_load_dwordx4 v[22:25], v[30:31] offset:2560
	flat_load_dwordx4 v[26:29], v[30:31] offset:3072
	s_nop 0
	flat_load_dwordx4 v[30:33], v[30:31] offset:3584
	s_lshl_b32 s38, s6, 4
	v_mov_b32_e32 v50, 0
	s_ashr_i32 s39, s38, 31
	s_mov_b64 s[44:45], -1
	s_mov_b32 s7, 0
	v_mov_b32_e32 v51, v50
	s_mov_b64 s[100:101], exec
	s_and_b64 exec, exec, s[42:43]
	v_mov_b64_e32 v[146:147], s[4:5]
	v_or_b32_e32 v150, 16, v57
	v_mad_i64_i32 v[148:149], s[34:35], v57, s20, v[146:147]
	v_mad_i64_i32 v[146:147], s[34:35], v150, s20, v[146:147]
	v_lshl_add_u64 v[148:149], s[38:39], 2, v[148:149]
	v_lshl_add_u64 v[146:147], s[38:39], 2, v[146:147]
	v_lshl_add_u64 v[148:149], v[148:149], 0, v[0:1]
	v_lshl_add_u64 v[146:147], v[146:147], 0, v[0:1]
	v_lshl_add_u64 v[150:151], v[148:149], 0, s[94:95]
	global_load_dwordx4 v[130:133], v[150:151], off offset:16
	v_lshl_add_u64 v[150:151], v[146:147], 0, s[94:95]
	global_load_dwordx4 v[138:141], v[150:151], off offset:16
	s_mov_b64 s[34:35], 0x12c01000
	v_lshl_add_u64 v[148:149], v[148:149], 0, s[34:35]
	v_lshl_add_u64 v[146:147], v[146:147], 0, s[34:35]
	global_load_dwordx4 v[134:137], v[148:149], off offset:2048
	global_load_dwordx4 v[142:145], v[146:147], off offset:2048
	s_mov_b64 exec, s[100:101]
	s_waitcnt vmcnt(0) lgkmcnt(0)
	v_cndmask_b32_e64 v5, v5, 0, s[40:41]
	v_cndmask_b32_e64 v4, v4, 0, s[40:41]
	v_cndmask_b32_e64 v3, v3, 0, s[40:41]
	v_cndmask_b32_e64 v2, v2, 0, s[40:41]
	v_cndmask_b32_e64 v9, v9, 0, s[40:41]
	v_cndmask_b32_e64 v8, v8, 0, s[40:41]
	v_cndmask_b32_e64 v7, v7, 0, s[40:41]
	v_cndmask_b32_e64 v6, v6, 0, s[40:41]
	v_cndmask_b32_e64 v13, v13, 0, s[40:41]
	v_cndmask_b32_e64 v12, v12, 0, s[40:41]
	v_cndmask_b32_e64 v11, v11, 0, s[40:41]
	v_cndmask_b32_e64 v10, v10, 0, s[40:41]
	v_cndmask_b32_e64 v17, v17, 0, s[40:41]
	v_cndmask_b32_e64 v16, v16, 0, s[40:41]
	v_cndmask_b32_e64 v15, v15, 0, s[40:41]
	v_cndmask_b32_e64 v14, v14, 0, s[40:41]
	v_cndmask_b32_e64 v21, v21, 0, s[40:41]
	v_cndmask_b32_e64 v20, v20, 0, s[40:41]
	v_cndmask_b32_e64 v19, v19, 0, s[40:41]
	v_cndmask_b32_e64 v18, v18, 0, s[40:41]
	v_cndmask_b32_e64 v25, v25, 0, s[40:41]
	v_cndmask_b32_e64 v24, v24, 0, s[40:41]
	v_cndmask_b32_e64 v23, v23, 0, s[40:41]
	v_cndmask_b32_e64 v22, v22, 0, s[40:41]
	v_cndmask_b32_e64 v29, v29, 0, s[40:41]
	v_cndmask_b32_e64 v28, v28, 0, s[40:41]
	v_cndmask_b32_e64 v27, v27, 0, s[40:41]
	v_cndmask_b32_e64 v26, v26, 0, s[40:41]
	v_cndmask_b32_e64 v33, v33, 0, s[40:41]
	v_cndmask_b32_e64 v32, v32, 0, s[40:41]
	v_cndmask_b32_e64 v31, v31, 0, s[40:41]
	v_cndmask_b32_e64 v30, v30, 0, s[40:41]
	v_pk_mov_b32 v[48:49], v[46:47], v[46:47] op_sel:[1,0]
	s_branch .LBB0_1050
.LBB0_1049:
	s_or_b64 exec, exec, s[46:47]
	v_mov_b32_e32 v130, v138
	v_mov_b32_e32 v131, v139
	v_mov_b32_e32 v132, v140
	v_mov_b32_e32 v133, v141
	v_mov_b32_e32 v134, v142
	v_mov_b32_e32 v135, v143
	v_mov_b32_e32 v136, v144
	v_mov_b32_e32 v137, v145
	v_mfma_f32_16x16x32_bf16 v[58:61], v[34:37], v[2:5], 0
	v_add_u32_e32 v74, 0x400, v54
	s_xor_b64 s[44:45], s[44:45], -1
	s_mov_b32 s7, 16
	v_mfma_f32_16x16x32_bf16 v[62:65], v[34:37], v[6:9], 0
	s_nop 7
	ds_write2_b32 v54, v58, v62 offset1:16
	ds_write2_b32 v54, v59, v63 offset0:132 offset1:148
	v_mfma_f32_16x16x32_bf16 v[70:73], v[34:37], v[14:17], 0
	ds_write2_b32 v74, v60, v64 offset0:8 offset1:24
	ds_write2_b32 v74, v61, v65 offset0:140 offset1:156
	s_nop 5
	ds_write2_b32 v55, v70, v71 offset1:132
	v_add_u32_e32 v62, 0x400, v55
	v_mfma_f32_16x16x32_bf16 v[66:69], v[34:37], v[10:13], 0
	s_andn2_b64 vcc, exec, s[44:45]
	s_mov_b64 s[44:45], 0
	v_mfma_f32_16x16x32_bf16 v[58:61], v[34:37], v[18:21], 0
	ds_write2_b32 v62, v72, v73 offset0:8 offset1:140
	s_nop 6
	ds_write2_b32 v54, v66, v58 offset0:32 offset1:64
	v_mfma_f32_16x16x32_bf16 v[62:65], v[34:37], v[22:25], 0
	ds_write2_b32 v54, v67, v59 offset0:164 offset1:196
	ds_write2_b32 v74, v68, v60 offset0:40 offset1:72
	ds_write2_b32 v74, v69, v61 offset0:172 offset1:204
	v_mfma_f32_16x16x32_bf16 v[58:61], v[34:37], v[26:29], 0
	s_nop 7
	ds_write2_b32 v54, v62, v58 offset0:80 offset1:96
	ds_write2_b32 v54, v63, v59 offset0:212 offset1:228
	ds_write2_b32 v74, v64, v60 offset0:88 offset1:104
	ds_write2_b32 v74, v65, v61 offset0:220 offset1:236
	v_mfma_f32_16x16x32_bf16 v[34:37], v[34:37], v[30:33], 0
	s_nop 7
	ds_write2_b32 v56, v34, v35 offset1:132
	v_add_u32_e32 v34, 0x400, v56
	ds_write2_b32 v34, v36, v37 offset0:8 offset1:140
	s_waitcnt lgkmcnt(0)
	v_add_u32_e32 v108, 16, v53
	v_add_u32_e32 v109, 32, v53
	v_add_u32_e32 v110, 48, v53
	v_add_u32_e32 v111, 64, v53
	v_add_u32_e32 v112, 80, v53
	v_add_u32_e32 v113, 96, v53
	v_add_u32_e32 v114, 112, v53
	v_add_u32_e32 v115, 128, v53
	v_add_u32_e32 v116, 144, v53
	v_add_u32_e32 v117, 160, v53
	v_add_u32_e32 v118, 176, v53
	v_add_u32_e32 v119, 192, v53
	v_add_u32_e32 v120, 208, v53
	v_add_u32_e32 v121, 224, v53
	v_add_u32_e32 v122, 240, v53
	ds_read2st64_b32 v[100:101], v53 offset0:0 offset1:1
	ds_read2st64_b32 v[102:103], v108 offset0:2 offset1:3
	ds_read2st64_b32 v[104:105], v109 offset0:4 offset1:5
	ds_read2st64_b32 v[106:107], v110 offset0:6 offset1:7
	s_waitcnt lgkmcnt(3)
	v_mul_f32_e32 v123, v47, v51
	v_fma_f32 v123, v46, v50, -v123
	v_mul_f32_e32 v124, v46, v51
	v_fmac_f32_e32 v124, v47, v50
	v_add_f32_e32 v125, v123, v100
	v_add_f32_e32 v126, v124, v101
	ds_read2st64_b32 v[100:101], v111 offset0:8 offset1:9
	s_waitcnt lgkmcnt(3)
	v_mul_f32_e32 v123, v47, v126
	v_fma_f32 v123, v46, v125, -v123
	v_mul_f32_e32 v124, v46, v126
	v_fmac_f32_e32 v124, v47, v125
	v_add_f32_e32 v127, v123, v102
	v_add_f32_e32 v128, v124, v103
	ds_read2st64_b32 v[102:103], v112 offset0:10 offset1:11
	s_waitcnt lgkmcnt(3)
	v_mul_f32_e32 v123, v47, v128
	v_fma_f32 v123, v46, v127, -v123
	v_mul_f32_e32 v124, v46, v128
	v_fmac_f32_e32 v124, v47, v127
	v_add_f32_e32 v125, v123, v104
	v_add_f32_e32 v126, v124, v105
	ds_read2st64_b32 v[104:105], v113 offset0:12 offset1:13
	s_waitcnt lgkmcnt(3)
	v_mul_f32_e32 v123, v47, v126
	v_fma_f32 v123, v46, v125, -v123
	v_mul_f32_e32 v124, v46, v126
	v_fmac_f32_e32 v124, v47, v125
	v_add_f32_e32 v127, v123, v106
	v_add_f32_e32 v128, v124, v107
	ds_read2st64_b32 v[106:107], v114 offset0:14 offset1:15
	s_waitcnt lgkmcnt(3)
	v_mul_f32_e32 v123, v47, v128
	v_fma_f32 v123, v46, v127, -v123
	v_mul_f32_e32 v124, v46, v128
	v_fmac_f32_e32 v124, v47, v127
	v_add_f32_e32 v125, v123, v100
	v_add_f32_e32 v126, v124, v101
	ds_read2st64_b32 v[100:101], v115 offset0:16 offset1:17
	s_waitcnt lgkmcnt(3)
	v_mul_f32_e32 v123, v47, v126
	v_fma_f32 v123, v46, v125, -v123
	v_mul_f32_e32 v124, v46, v126
	v_fmac_f32_e32 v124, v47, v125
	v_add_f32_e32 v127, v123, v102
	v_add_f32_e32 v128, v124, v103
	ds_read2st64_b32 v[102:103], v116 offset0:18 offset1:19
	s_waitcnt lgkmcnt(3)
	v_mul_f32_e32 v123, v47, v128
	v_fma_f32 v123, v46, v127, -v123
	v_mul_f32_e32 v124, v46, v128
	v_fmac_f32_e32 v124, v47, v127
	v_add_f32_e32 v125, v123, v104
	v_add_f32_e32 v126, v124, v105
	ds_read2st64_b32 v[104:105], v117 offset0:20 offset1:21
	s_waitcnt lgkmcnt(3)
	v_mul_f32_e32 v123, v47, v126
	v_fma_f32 v123, v46, v125, -v123
	v_mul_f32_e32 v124, v46, v126
	v_fmac_f32_e32 v124, v47, v125
	v_add_f32_e32 v127, v123, v106
	v_add_f32_e32 v128, v124, v107
	ds_read2st64_b32 v[106:107], v118 offset0:22 offset1:23
	s_waitcnt lgkmcnt(3)
	v_mul_f32_e32 v123, v47, v128
	v_fma_f32 v123, v46, v127, -v123
	v_mul_f32_e32 v124, v46, v128
	v_fmac_f32_e32 v124, v47, v127
	v_add_f32_e32 v125, v123, v100
	v_add_f32_e32 v126, v124, v101
	ds_read2st64_b32 v[100:101], v119 offset0:24 offset1:25
	s_waitcnt lgkmcnt(3)
	v_mul_f32_e32 v123, v47, v126
	v_fma_f32 v123, v46, v125, -v123
	v_mul_f32_e32 v124, v46, v126
	v_fmac_f32_e32 v124, v47, v125
	v_add_f32_e32 v127, v123, v102
	v_add_f32_e32 v128, v124, v103
	ds_read2st64_b32 v[102:103], v120 offset0:26 offset1:27
	s_waitcnt lgkmcnt(3)
	v_mul_f32_e32 v123, v47, v128
	v_fma_f32 v123, v46, v127, -v123
	v_mul_f32_e32 v124, v46, v128
	v_fmac_f32_e32 v124, v47, v127
	v_add_f32_e32 v125, v123, v104
	v_add_f32_e32 v126, v124, v105
	ds_read2st64_b32 v[104:105], v121 offset0:28 offset1:29
	s_waitcnt lgkmcnt(3)
	v_mul_f32_e32 v123, v47, v126
	v_fma_f32 v123, v46, v125, -v123
	v_mul_f32_e32 v124, v46, v126
	v_fmac_f32_e32 v124, v47, v125
	v_add_f32_e32 v127, v123, v106
	v_add_f32_e32 v128, v124, v107
	ds_read2st64_b32 v[106:107], v122 offset0:30 offset1:31
	s_waitcnt lgkmcnt(3)
	v_mul_f32_e32 v123, v47, v128
	v_fma_f32 v123, v46, v127, -v123
	v_mul_f32_e32 v124, v46, v128
	v_fmac_f32_e32 v124, v47, v127
	v_add_f32_e32 v125, v123, v100
	v_add_f32_e32 v126, v124, v101
	s_waitcnt lgkmcnt(2)
	v_mul_f32_e32 v123, v47, v126
	v_fma_f32 v123, v46, v125, -v123
	v_mul_f32_e32 v124, v46, v126
	v_fmac_f32_e32 v124, v47, v125
	v_add_f32_e32 v127, v123, v102
	v_add_f32_e32 v128, v124, v103
	s_waitcnt lgkmcnt(1)
	v_mul_f32_e32 v123, v47, v128
	v_fma_f32 v123, v46, v127, -v123
	v_mul_f32_e32 v124, v46, v128
	v_fmac_f32_e32 v124, v47, v127
	v_add_f32_e32 v125, v123, v104
	v_add_f32_e32 v126, v124, v105
	s_waitcnt lgkmcnt(0)
	v_mul_f32_e32 v123, v47, v126
	v_fma_f32 v123, v46, v125, -v123
	v_mul_f32_e32 v124, v46, v126
	v_fmac_f32_e32 v124, v47, v125
	v_add_f32_e32 v50, v123, v106
	v_add_f32_e32 v51, v124, v107
	s_cbranch_vccz .LBB0_1047
.LBB0_1050:
	v_mov_b32_e32 v34, 0
	v_mov_b32_e32 v35, 0
	v_mov_b32_e32 v36, 0
	v_mov_b32_e32 v37, 0
	s_and_saveexec_b64 s[46:47], s[42:43]
	s_cbranch_execz .LBB0_1049
	v_or_b32_e32 v36, s7, v57
	v_mov_b64_e32 v[34:35], s[4:5]
	v_mad_i64_i32 v[34:35], s[34:35], v36, s20, v[34:35]
	v_lshl_add_u64 v[34:35], s[38:39], 2, v[34:35]
	v_lshl_add_u64 v[58:59], v[34:35], 0, v[0:1]
	v_lshl_add_u64 v[34:35], v[58:59], 0, s[94:95]
	v_add_co_u32_e32 v58, vcc, 0x12c01000, v58
	s_waitcnt lgkmcnt(0)
	v_mov_b32_e32 v34, v130
	v_mov_b32_e32 v35, v131
	v_mov_b32_e32 v36, v132
	v_mov_b32_e32 v37, v133
	v_mov_b32_e32 v58, v134
	v_mov_b32_e32 v59, v135
	v_mov_b32_e32 v60, v136
	v_mov_b32_e32 v61, v137
	v_and_b32_sdwa v64, v37, v225 dst_sel:DWORD dst_unused:UNUSED_PAD src0_sel:WORD_1 src1_sel:DWORD
	v_and_b32_sdwa v65, v36, v225 dst_sel:DWORD dst_unused:UNUSED_PAD src0_sel:WORD_1 src1_sel:DWORD
	v_bfe_u32 v63, v58, 16, 1
	v_add3_u32 v62, v36, v65, s23
	v_add3_u32 v37, v37, v64, s23
	v_bfe_u32 v64, v59, 16, 1
	v_cvt_pk_bf16_f32 v36, v34, v35
	v_add3_u32 v34, v58, v63, s23
	v_add3_u32 v58, v59, v64, s23
	v_lshrrev_b32_e32 v34, 16, v34
	v_cvt_pk_bf16_f32 v35, v60, v61
	v_and_or_b32 v34, v58, s15, v34
	v_perm_b32 v37, v37, v62, s22
	s_branch .LBB0_1049
